# RWKV scan waves: one static s_setprio 3 per chunk entry (reset to 0 after the scan) so the serial scan chain outranks the loader waves
# baseline (speedup 1.0000x reference)
; #define LAS __attribute__((address_space(3)))
; template <bool SAMPLE>
; __device__ __forceinline__ void rwkv_unit(PR P, LAS float* lds, const int b, const int h, const int half, const int wv) {
;     ...
;     for (int c = 0; c < NCH; ++c) {
;         LAS float* cur = (c & 1) ? buf1 : buf0; LAS float* nxt = (c & 1) ? buf0 : buf1;
;         if (c + 1 < NCH) RW_LOAD(c + 1);
;         if (wid < 4) {
;             constexpr int GS = SAMPLE ? 4 : 16;
;             for (int g = 0; g < TC / GS; ++g) {
;                 float yk0 = 0.f, yk1 = 0.f;
;                 const LAS float* q0 = cur + (g * GS) * 384;
;                 f32x4 r4 = *(const LAS f32x4*)(q0 + j0), o4 = *(const LAS f32x4*)(q0 + 64 + j0), k4 = *(const LAS f32x4*)(q0 + 128 + j0), a4 = *(const LAS f32x4*)(q0 + 192 + j0), b4 = *(const LAS f32x4*)(q0 + 256 + j0);
;                 f32x2 v2 = *(const LAS f32x2*)(q0 + 320 + row0);
;                 float py0 = 0.f, py1 = 0.f;
; #pragma unroll
;                 for (int tt = 0; tt < GS; ++tt) {
;                     const LAS float* qn = q0 + (tt + 1 < GS ? tt + 1 : tt) * 384;
;                     const f32x4 nr4 = *(const LAS f32x4*)(qn + j0), no4 = *(const LAS f32x4*)(qn + 64 + j0), nk4 = *(const LAS f32x4*)(qn + 128 + j0), na4 = *(const LAS f32x4*)(qn + 192 + j0), nb4 = *(const LAS f32x4*)(qn + 256 + j0);
;                     const f32x2 nv2 = *(const LAS f32x2*)(qn + 320 + row0);
;                     f32x2 sa = (S[0] * a4[0] + S[1] * a4[1]) + (S[2] * a4[2] + S[3] * a4[3]);
;                     float sx = sa.x, sy = sa.y; ROW16_SUM4(sx, sy, py0, py1); sa = (f32x2){sx, sy};
;                     if (tt > 0) { yk0 = cgl == tt - 1 ? py0 : yk0; yk1 = cgl == tt - 1 ? py1 : yk1; }
; #pragma unroll
;                     for (int c = 0; c < 4; ++c) { f32x2 t = S[c] - S[c] * o4[c]; t = t + sa * b4[c]; S[c] = t + v2 * k4[c]; }
;                     const f32x2 y = (S[0] * r4[0] + S[1] * r4[1]) + (S[2] * r4[2] + S[3] * r4[3]);
;                     py0 = y.x; py1 = y.y;
;                     r4 = nr4; o4 = no4; k4 = nk4; a4 = na4; b4 = nb4; v2 = nv2;
;                 }
;                 ROW16_SUM2(py0, py1); yk0 = cgl == GS - 1 ? py0 : yk0; yk1 = cgl == GS - 1 ? py1 : yk1;
;                 if (cgl < GS) *(unsigned*)(YS + (size_t)(row_base + c * TC + g * GS + cgl) * 512 + h * 64 + row0) = pg8::cvt_pk_bf16(yk0, yk1);
.Lrw_scan_chunk:
	s_setprio 3
	s_add_i32 s56, s71, 1
	s_bitcmp0_b32 s71, 0
	s_cselect_b32 s57, 0, s55
	v_lshl_add_u32 v57, s71, 5, v77
	.p2alignl 3, 3212836864
	v_lshl_add_u32 v152, v76, 2, s57
	v_lshl_add_u32 v153, v54, 2, s57
	v_add_u32_e32 v153, 0x100, v153
	s_mov_b32 s98, 0xff00ff00
	s_mov_b32 s99, 0xff00ff00
	v_xor_b32_e32 v156, 0x80, v153
	v_cndmask_b32_e64 v153, v153, v156, s[98:99]
	ds_read_b128 v[172:175], v152 offset:768
	ds_read_b128 v[164:167], v152 offset:256
	ds_read2st64_b64 v[240:243], v153 offset0:2 offset1:5
	ds_read_b128 v[168:171], v152 offset:512
	ds_read_b128 v[192:195], v152 offset:2304
	ds_read_b128 v[184:187], v152 offset:1792
	ds_read_b128 v[176:179], v152 offset:1024
	ds_read_b128 v[188:191], v152 offset:2048
	ds_read_b128 v[196:199], v152 offset:2560
	ds_read_b128 v[160:163], v152 offset:0
	ds_read_b128 v[180:183], v152 offset:1536
	s_cmp_eq_u32 s71, 0
	s_cbranch_scc1 .Lrw_first_chunk
	v_add_f32_dpp v110, v111, v110 row_ror:8 row_mask:0xf bank_mask:0x3 bound_ctrl:1
	v_add_f32_dpp v112, v113, v112 row_ror:8 row_mask:0xf bank_mask:0x3 bound_ctrl:1
	v_add_f32_dpp v114, v115, v114 row_ror:8 row_mask:0xf bank_mask:0x3 bound_ctrl:1
	v_add_f32_dpp v116, v117, v116 row_ror:8 row_mask:0xf bank_mask:0x3 bound_ctrl:1
	v_add_f32_dpp v118, v119, v118 row_ror:8 row_mask:0xf bank_mask:0x3 bound_ctrl:1
	v_add_f32_dpp v120, v121, v120 row_ror:8 row_mask:0xf bank_mask:0x3 bound_ctrl:1
	v_add_f32_dpp v122, v123, v122 row_ror:8 row_mask:0xf bank_mask:0x3 bound_ctrl:1
	v_add_f32_dpp v124, v125, v124 row_ror:8 row_mask:0xf bank_mask:0x3 bound_ctrl:1
	v_add_f32_dpp v111, v110, v111 row_ror:8 row_mask:0xf bank_mask:0x3 bound_ctrl:1
	v_add_f32_dpp v113, v112, v113 row_ror:8 row_mask:0xf bank_mask:0x3 bound_ctrl:1
	v_add_f32_dpp v115, v114, v115 row_ror:8 row_mask:0xf bank_mask:0x3 bound_ctrl:1
	v_add_f32_dpp v117, v116, v117 row_ror:8 row_mask:0xf bank_mask:0x3 bound_ctrl:1
	v_add_f32_dpp v119, v118, v119 row_ror:8 row_mask:0xf bank_mask:0x3 bound_ctrl:1
	v_add_f32_dpp v121, v120, v121 row_ror:8 row_mask:0xf bank_mask:0x3 bound_ctrl:1
	v_add_f32_dpp v123, v122, v123 row_ror:8 row_mask:0xf bank_mask:0x3 bound_ctrl:1
	v_add_f32_dpp v125, v124, v125 row_ror:8 row_mask:0xf bank_mask:0x3 bound_ctrl:1
	v_add_f32_dpp v110, v127, v126 row_ror:8 row_mask:0xf bank_mask:0xc bound_ctrl:1
	v_add_f32_dpp v112, v129, v128 row_ror:8 row_mask:0xf bank_mask:0xc bound_ctrl:1
	v_add_f32_dpp v114, v131, v130 row_ror:8 row_mask:0xf bank_mask:0xc bound_ctrl:1
	v_add_f32_dpp v116, v133, v132 row_ror:8 row_mask:0xf bank_mask:0xc bound_ctrl:1
	v_add_f32_dpp v118, v135, v134 row_ror:8 row_mask:0xf bank_mask:0xc bound_ctrl:1
	v_add_f32_dpp v120, v137, v136 row_ror:8 row_mask:0xf bank_mask:0xc bound_ctrl:1
	v_add_f32_dpp v122, v139, v138 row_ror:8 row_mask:0xf bank_mask:0xc bound_ctrl:1
	v_add_f32_dpp v124, v141, v140 row_ror:8 row_mask:0xf bank_mask:0xc bound_ctrl:1
	v_add_f32_dpp v111, v126, v127 row_ror:8 row_mask:0xf bank_mask:0xc bound_ctrl:1
	v_add_f32_dpp v113, v128, v129 row_ror:8 row_mask:0xf bank_mask:0xc bound_ctrl:1
	v_add_f32_dpp v115, v130, v131 row_ror:8 row_mask:0xf bank_mask:0xc bound_ctrl:1
	v_add_f32_dpp v117, v132, v133 row_ror:8 row_mask:0xf bank_mask:0xc bound_ctrl:1
	v_add_f32_dpp v119, v134, v135 row_ror:8 row_mask:0xf bank_mask:0xc bound_ctrl:1
	v_add_f32_dpp v121, v136, v137 row_ror:8 row_mask:0xf bank_mask:0xc bound_ctrl:1
	v_add_f32_dpp v123, v138, v139 row_ror:8 row_mask:0xf bank_mask:0xc bound_ctrl:1
	v_add_f32_dpp v125, v140, v141 row_ror:8 row_mask:0xf bank_mask:0xc bound_ctrl:1
	v_add_f32_dpp v110, v110, v110 row_shl:4 row_mask:0xf bank_mask:0x5 bound_ctrl:1
	v_add_f32_dpp v110, v118, v118 row_shr:4 row_mask:0xf bank_mask:0xa bound_ctrl:1
	v_add_f32_dpp v112, v112, v112 row_shl:4 row_mask:0xf bank_mask:0x5 bound_ctrl:1
	v_add_f32_dpp v112, v120, v120 row_shr:4 row_mask:0xf bank_mask:0xa bound_ctrl:1
	v_add_f32_dpp v114, v114, v114 row_shl:4 row_mask:0xf bank_mask:0x5 bound_ctrl:1
	v_add_f32_dpp v114, v122, v122 row_shr:4 row_mask:0xf bank_mask:0xa bound_ctrl:1
	v_add_f32_dpp v116, v116, v116 row_shl:4 row_mask:0xf bank_mask:0x5 bound_ctrl:1
	v_add_f32_dpp v116, v124, v124 row_shr:4 row_mask:0xf bank_mask:0xa bound_ctrl:1
	v_add_f32_dpp v111, v111, v111 row_shl:4 row_mask:0xf bank_mask:0x5 bound_ctrl:1
	v_add_f32_dpp v111, v119, v119 row_shr:4 row_mask:0xf bank_mask:0xa bound_ctrl:1
	v_add_f32_dpp v113, v113, v113 row_shl:4 row_mask:0xf bank_mask:0x5 bound_ctrl:1
	v_add_f32_dpp v113, v121, v121 row_shr:4 row_mask:0xf bank_mask:0xa bound_ctrl:1
	v_add_f32_dpp v115, v115, v115 row_shl:4 row_mask:0xf bank_mask:0x5 bound_ctrl:1
	v_add_f32_dpp v115, v123, v123 row_shr:4 row_mask:0xf bank_mask:0xa bound_ctrl:1
	v_add_f32_dpp v117, v117, v117 row_shl:4 row_mask:0xf bank_mask:0x5 bound_ctrl:1
	v_add_f32_dpp v117, v125, v125 row_shr:4 row_mask:0xf bank_mask:0xa bound_ctrl:1
	v_add_f32_dpp v110, v110, v110 quad_perm:[1,0,3,2] row_mask:0xf bank_mask:0xf bound_ctrl:1
	v_add_f32_dpp v112, v112, v112 quad_perm:[1,0,3,2] row_mask:0xf bank_mask:0xf bound_ctrl:1
	v_add_f32_dpp v114, v114, v114 quad_perm:[1,0,3,2] row_mask:0xf bank_mask:0xf bound_ctrl:1
	v_add_f32_dpp v116, v116, v116 quad_perm:[1,0,3,2] row_mask:0xf bank_mask:0xf bound_ctrl:1
	v_add_f32_dpp v111, v111, v111 quad_perm:[1,0,3,2] row_mask:0xf bank_mask:0xf bound_ctrl:1
	v_add_f32_dpp v113, v113, v113 quad_perm:[1,0,3,2] row_mask:0xf bank_mask:0xf bound_ctrl:1
	v_add_f32_dpp v115, v115, v115 quad_perm:[1,0,3,2] row_mask:0xf bank_mask:0xf bound_ctrl:1
	v_add_f32_dpp v117, v117, v117 quad_perm:[1,0,3,2] row_mask:0xf bank_mask:0xf bound_ctrl:1
	v_add_f32_dpp v110, v110, v110 quad_perm:[2,3,0,1] row_mask:0xf bank_mask:0xf bound_ctrl:1
	v_add_f32_dpp v112, v112, v112 quad_perm:[2,3,0,1] row_mask:0xf bank_mask:0xf bound_ctrl:1
	v_add_f32_dpp v114, v114, v114 quad_perm:[2,3,0,1] row_mask:0xf bank_mask:0xf bound_ctrl:1
	v_add_f32_dpp v116, v116, v116 quad_perm:[2,3,0,1] row_mask:0xf bank_mask:0xf bound_ctrl:1
	v_add_f32_dpp v111, v111, v111 quad_perm:[2,3,0,1] row_mask:0xf bank_mask:0xf bound_ctrl:1
	v_add_f32_dpp v113, v113, v113 quad_perm:[2,3,0,1] row_mask:0xf bank_mask:0xf bound_ctrl:1
	v_add_f32_dpp v115, v115, v115 quad_perm:[2,3,0,1] row_mask:0xf bank_mask:0xf bound_ctrl:1
	v_add_f32_dpp v117, v117, v117 quad_perm:[2,3,0,1] row_mask:0xf bank_mask:0xf bound_ctrl:1
	v_subrev_u32_e32 v72, 16, v57
	v_ashrrev_i32_e32 v73, 31, v72
	v_lshlrev_b64 v[72:73], 10, v[72:73]
	v_lshl_add_u64 v[72:73], v[64:65], 0, v[72:73]
	v_cndmask_b32_e64 v154, v116, v114, s[16:17]
	v_cndmask_b32_e64 v155, v117, v115, s[16:17]
	v_cndmask_b32_e64 v154, v154, v112, s[14:15]
	v_cndmask_b32_e64 v155, v155, v113, s[14:15]
	v_cndmask_b32_e64 v154, v154, v110, s[12:13]
	v_cndmask_b32_e64 v155, v155, v111, s[12:13]
	v_cvt_pk_bf16_f32 v157, v155, v154
	v_cvt_pk_bf16_f32 v154, v154, v155
	v_cndmask_b32_e64 v154, v154, v157, s[98:99]
	global_store_dword v[72:73], v154, off

; #define RW_PROC(dst) do { RW_PROC1(dst, 0); RW_PROC1(dst, 1); } while (0)
; template <bool SAMPLE>
; __device__ __forceinline__ void rwkv_unit(PR P, LAS float* lds, const int b, const int h, const int half, const int wv) {
;     ...
;         }
;         if (c + 1 < NCH) RW_PROC(nxt);
;         __syncthreads();
;     }
;     if (wid < 4) { *(float4*)sout = make_float4(S[0].x, S[1].x, S[2].x, S[3].x); *(float4*)(sout + 64) = make_float4(S[0].y, S[1].y, S[2].y, S[3].y); }
.LBB0_723:
	s_setprio 0
	s_nop 0
	s_and_saveexec_b64 s[10:11], s[8:9]
	s_cbranch_execz .LBB0_725
; __device__ __forceinline__ unsigned cvt_pk_bf16(float lo, float hi) { const f32x2_t v = {lo, hi}; const bf16x2_t b = __builtin_convertvector(v, bf16x2_t); return __builtin_bit_cast(unsigned, b); }
; #define ROW16_SUM2(x, y) do { DPP2(x, y, "quad_perm:[1,0,3,2]", "s_nop 1"); DPP2(x, y, "quad_perm:[2,3,0,1]", "s_nop 0"); DPP2(x, y, "row_half_mirror", "s_nop 0"); DPP2(x, y, "row_mirror", "s_nop 0"); } while (0)
; template <bool SAMPLE>
; __device__ __forceinline__ void rwkv_unit(PR P, LAS float* lds, const int b, const int h, const int half, const int wv) {
;     ...
;                 ROW16_SUM2(py0, py1); yk0 = cgl == GS - 1 ? py0 : yk0; yk1 = cgl == GS - 1 ? py1 : yk1;
;                 if (cgl < GS) *(unsigned*)(YS + (size_t)(row_base + c * TC + g * GS + cgl) * 512 + h * 64 + row0) = pg8::cvt_pk_bf16(yk0, yk1);
;     ...
;     if (wid < 4) { *(float4*)sout = make_float4(S[0].x, S[1].x, S[2].x, S[3].x); *(float4*)(sout + 64) = make_float4(S[0].y, S[1].y, S[2].y, S[3].y); }
	v_add_f32_dpp v110, v111, v110 row_ror:8 row_mask:0xf bank_mask:0x3 bound_ctrl:1
	v_add_f32_dpp v112, v113, v112 row_ror:8 row_mask:0xf bank_mask:0x3 bound_ctrl:1
	v_add_f32_dpp v114, v115, v114 row_ror:8 row_mask:0xf bank_mask:0x3 bound_ctrl:1
	v_add_f32_dpp v116, v117, v116 row_ror:8 row_mask:0xf bank_mask:0x3 bound_ctrl:1
	v_add_f32_dpp v118, v119, v118 row_ror:8 row_mask:0xf bank_mask:0x3 bound_ctrl:1
	v_add_f32_dpp v120, v121, v120 row_ror:8 row_mask:0xf bank_mask:0x3 bound_ctrl:1
	v_add_f32_dpp v122, v123, v122 row_ror:8 row_mask:0xf bank_mask:0x3 bound_ctrl:1
	v_add_f32_dpp v124, v125, v124 row_ror:8 row_mask:0xf bank_mask:0x3 bound_ctrl:1
	v_add_f32_dpp v111, v110, v111 row_ror:8 row_mask:0xf bank_mask:0x3 bound_ctrl:1
	v_add_f32_dpp v113, v112, v113 row_ror:8 row_mask:0xf bank_mask:0x3 bound_ctrl:1
	v_add_f32_dpp v115, v114, v115 row_ror:8 row_mask:0xf bank_mask:0x3 bound_ctrl:1
	v_add_f32_dpp v117, v116, v117 row_ror:8 row_mask:0xf bank_mask:0x3 bound_ctrl:1
	v_add_f32_dpp v119, v118, v119 row_ror:8 row_mask:0xf bank_mask:0x3 bound_ctrl:1
	v_add_f32_dpp v121, v120, v121 row_ror:8 row_mask:0xf bank_mask:0x3 bound_ctrl:1
	v_add_f32_dpp v123, v122, v123 row_ror:8 row_mask:0xf bank_mask:0x3 bound_ctrl:1
	v_add_f32_dpp v125, v124, v125 row_ror:8 row_mask:0xf bank_mask:0x3 bound_ctrl:1
	v_add_f32_dpp v110, v127, v126 row_ror:8 row_mask:0xf bank_mask:0xc bound_ctrl:1
	v_add_f32_dpp v112, v129, v128 row_ror:8 row_mask:0xf bank_mask:0xc bound_ctrl:1
	v_add_f32_dpp v114, v131, v130 row_ror:8 row_mask:0xf bank_mask:0xc bound_ctrl:1
	v_add_f32_dpp v116, v133, v132 row_ror:8 row_mask:0xf bank_mask:0xc bound_ctrl:1
	v_add_f32_dpp v118, v135, v134 row_ror:8 row_mask:0xf bank_mask:0xc bound_ctrl:1
	v_add_f32_dpp v120, v137, v136 row_ror:8 row_mask:0xf bank_mask:0xc bound_ctrl:1
	v_add_f32_dpp v122, v139, v138 row_ror:8 row_mask:0xf bank_mask:0xc bound_ctrl:1
	v_add_f32_dpp v124, v141, v140 row_ror:8 row_mask:0xf bank_mask:0xc bound_ctrl:1
	v_add_f32_dpp v111, v126, v127 row_ror:8 row_mask:0xf bank_mask:0xc bound_ctrl:1
	v_add_f32_dpp v113, v128, v129 row_ror:8 row_mask:0xf bank_mask:0xc bound_ctrl:1
	v_add_f32_dpp v115, v130, v131 row_ror:8 row_mask:0xf bank_mask:0xc bound_ctrl:1
	v_add_f32_dpp v117, v132, v133 row_ror:8 row_mask:0xf bank_mask:0xc bound_ctrl:1
	v_add_f32_dpp v119, v134, v135 row_ror:8 row_mask:0xf bank_mask:0xc bound_ctrl:1
	v_add_f32_dpp v121, v136, v137 row_ror:8 row_mask:0xf bank_mask:0xc bound_ctrl:1
	v_add_f32_dpp v123, v138, v139 row_ror:8 row_mask:0xf bank_mask:0xc bound_ctrl:1
	v_add_f32_dpp v125, v140, v141 row_ror:8 row_mask:0xf bank_mask:0xc bound_ctrl:1
	v_add_f32_dpp v110, v110, v110 row_shl:4 row_mask:0xf bank_mask:0x5 bound_ctrl:1
	v_add_f32_dpp v110, v118, v118 row_shr:4 row_mask:0xf bank_mask:0xa bound_ctrl:1
	v_add_f32_dpp v112, v112, v112 row_shl:4 row_mask:0xf bank_mask:0x5 bound_ctrl:1
	v_add_f32_dpp v112, v120, v120 row_shr:4 row_mask:0xf bank_mask:0xa bound_ctrl:1
	v_add_f32_dpp v114, v114, v114 row_shl:4 row_mask:0xf bank_mask:0x5 bound_ctrl:1
	v_add_f32_dpp v114, v122, v122 row_shr:4 row_mask:0xf bank_mask:0xa bound_ctrl:1
	v_add_f32_dpp v116, v116, v116 row_shl:4 row_mask:0xf bank_mask:0x5 bound_ctrl:1
	v_add_f32_dpp v116, v124, v124 row_shr:4 row_mask:0xf bank_mask:0xa bound_ctrl:1
	v_add_f32_dpp v111, v111, v111 row_shl:4 row_mask:0xf bank_mask:0x5 bound_ctrl:1
	v_add_f32_dpp v111, v119, v119 row_shr:4 row_mask:0xf bank_mask:0xa bound_ctrl:1
	v_add_f32_dpp v113, v113, v113 row_shl:4 row_mask:0xf bank_mask:0x5 bound_ctrl:1
	v_add_f32_dpp v113, v121, v121 row_shr:4 row_mask:0xf bank_mask:0xa bound_ctrl:1
	v_add_f32_dpp v115, v115, v115 row_shl:4 row_mask:0xf bank_mask:0x5 bound_ctrl:1
	v_add_f32_dpp v115, v123, v123 row_shr:4 row_mask:0xf bank_mask:0xa bound_ctrl:1
	v_add_f32_dpp v117, v117, v117 row_shl:4 row_mask:0xf bank_mask:0x5 bound_ctrl:1
	v_add_f32_dpp v117, v125, v125 row_shr:4 row_mask:0xf bank_mask:0xa bound_ctrl:1
	v_add_f32_dpp v110, v110, v110 quad_perm:[1,0,3,2] row_mask:0xf bank_mask:0xf bound_ctrl:1
	v_add_f32_dpp v112, v112, v112 quad_perm:[1,0,3,2] row_mask:0xf bank_mask:0xf bound_ctrl:1
	v_add_f32_dpp v114, v114, v114 quad_perm:[1,0,3,2] row_mask:0xf bank_mask:0xf bound_ctrl:1
	v_add_f32_dpp v116, v116, v116 quad_perm:[1,0,3,2] row_mask:0xf bank_mask:0xf bound_ctrl:1
	v_add_f32_dpp v111, v111, v111 quad_perm:[1,0,3,2] row_mask:0xf bank_mask:0xf bound_ctrl:1
	v_add_f32_dpp v113, v113, v113 quad_perm:[1,0,3,2] row_mask:0xf bank_mask:0xf bound_ctrl:1
	v_add_f32_dpp v115, v115, v115 quad_perm:[1,0,3,2] row_mask:0xf bank_mask:0xf bound_ctrl:1
	v_add_f32_dpp v117, v117, v117 quad_perm:[1,0,3,2] row_mask:0xf bank_mask:0xf bound_ctrl:1
	v_add_f32_dpp v110, v110, v110 quad_perm:[2,3,0,1] row_mask:0xf bank_mask:0xf bound_ctrl:1
	v_add_f32_dpp v112, v112, v112 quad_perm:[2,3,0,1] row_mask:0xf bank_mask:0xf bound_ctrl:1
	v_add_f32_dpp v114, v114, v114 quad_perm:[2,3,0,1] row_mask:0xf bank_mask:0xf bound_ctrl:1
	v_add_f32_dpp v116, v116, v116 quad_perm:[2,3,0,1] row_mask:0xf bank_mask:0xf bound_ctrl:1
	v_add_f32_dpp v111, v111, v111 quad_perm:[2,3,0,1] row_mask:0xf bank_mask:0xf bound_ctrl:1
	v_add_f32_dpp v113, v113, v113 quad_perm:[2,3,0,1] row_mask:0xf bank_mask:0xf bound_ctrl:1
	v_add_f32_dpp v115, v115, v115 quad_perm:[2,3,0,1] row_mask:0xf bank_mask:0xf bound_ctrl:1
	v_add_f32_dpp v117, v117, v117 quad_perm:[2,3,0,1] row_mask:0xf bank_mask:0xf bound_ctrl:1
	v_add_u32_e32 v72, 16, v57
	v_ashrrev_i32_e32 v73, 31, v72
	v_lshlrev_b64 v[72:73], 10, v[72:73]
	v_lshl_add_u64 v[72:73], v[64:65], 0, v[72:73]
	v_cndmask_b32_e64 v154, v116, v114, s[16:17]
	v_cndmask_b32_e64 v155, v117, v115, s[16:17]
	v_cndmask_b32_e64 v154, v154, v112, s[14:15]
	v_cndmask_b32_e64 v155, v155, v113, s[14:15]
	v_cndmask_b32_e64 v154, v154, v110, s[12:13]
	v_cndmask_b32_e64 v155, v155, v111, s[12:13]
	v_cvt_pk_bf16_f32 v157, v155, v154
	v_cvt_pk_bf16_f32 v154, v154, v155
	v_cndmask_b32_e64 v154, v154, v157, s[98:99]
	global_store_dword v[72:73], v154, off
	s_lshl_b32 s5, s5, 3
	s_or_b32 s4, s5, s4
	s_ashr_i32 s5, s4, 31
	s_lshl_b64 s[4:5], s[4:5], 14
	s_add_u32 s4, s44, s4
	s_addc_u32 s5, s45, s5
	s_waitcnt vmcnt(4)
	v_lshlrev_b32_e32 v0, 8, v54
	v_mov_b32_e32 v1, 0
	v_lshl_add_u64 v[2:3], s[4:5], 0, v[0:1]
	v_lshlrev_b32_e32 v0, 2, v76
	s_waitcnt vmcnt(3)
	v_lshl_add_u64 v[4:5], v[2:3], 0, v[0:1]
	s_mov_b64 s[4:5], 0x4208000
	v_lshl_add_u64 v[6:7], v[4:5], 0, s[4:5]
	v_add_co_u32_e32 v4, vcc, 0x4208000, v4
	v_mov_b32_e32 v0, v66
	v_mov_b32_e32 v1, v20
	v_mov_b32_e32 v2, v68
	v_mov_b32_e32 v3, v70
	v_addc_co_u32_e32 v5, vcc, 0, v5, vcc
	v_mov_b32_e32 v20, v67
	v_mov_b32_e32 v22, v69
	v_mov_b32_e32 v23, v71
	v_mov_b32_e32 v8, 0x100
	v_mov_b32_e32 v11, 0
	v_cndmask_b32_e64 v10, 0, v8, s[98:99]
	v_lshl_add_u64 v[4:5], v[4:5], 0, v[10:11]
	v_sub_co_u32_e32 v6, vcc, v6, v10
	s_nop 1
	v_subbrev_co_u32_e32 v7, vcc, 0, v7, vcc
	global_store_dwordx4 v[4:5], v[0:3], off
	global_store_dwordx4 v[6:7], v[20:23], off offset:256
